# code placement: 4-byte pad so the three big GEMM K-loop heads sit on 8-byte phase 0 as in the baseline
# baseline (speedup 1.0000x reference)
; #define PG8_STAGE(bufoff, gbase, voff) do { _Pragma("unroll") for (int _i = 0; _i < 2; ++_i) \
;         __builtin_amdgcn_global_load_lds((const unsigned*)((const char*)(gbase) + (voff)[_i]), (PG8_LAS unsigned*)(lds + (bufoff) + ldsw + _i * 8192), 16, 0, 0); } while (0)
; #define PG8_LDA(dst, b, h) do { _Pragma("unroll") for (int m = 0; m < 4; ++m) _Pragma("unroll") for (int k = 0; k < 2; ++k) dst[m][k] = *(const PG8_LAS bf16x8*)(lds + PG8_SA(b, h) + aoff + m * 2048 + k * 1024); } while (0)
; #define PG8_LDB(dst, b, h) do { _Pragma("unroll") for (int n = 0; n < 2; ++n) _Pragma("unroll") for (int k = 0; k < 2; ++k) dst[n][k] = *(const PG8_LAS bf16x8*)(lds + PG8_SB(b, h) + boff + n * 2048 + k * 1024); } while (0)
; #define PG8_MMA(ai, bj, At, Bt) do { __builtin_amdgcn_s_setprio(1); _Pragma("unroll") for (int m = 0; m < 4; ++m) _Pragma("unroll") for (int n = 0; n < 2; ++n) _Pragma("unroll") for (int k = 0; k < 2; ++k) \
;         acc[ai][bj][m][n] = __builtin_amdgcn_mfma_f32_16x16x32_bf16(Bt[n][k], At[m][k], acc[ai][bj][m][n], 0, 0, 0); __builtin_amdgcn_s_setprio(0); } while (0)
; #define PG8_WAIT_V(n) asm volatile("s_waitcnt vmcnt(" #n ")" ::: "memory")
; #define PG8_WAIT_L(n) asm volatile("s_waitcnt lgkmcnt(" #n ")" ::: "memory")
; template <class Epi, class Sched, bool ALIGN_EPI = false, bool SP2 = false>
; __device__ __forceinline__ void gemm_phase(PG8_LAS unsigned char* lds, const Gemm g, const Sched& S, const Epi& E) {
;     ...
;             const bool last = (t == nt - 2);
;             const char* a1 = cA + (size_t)(t + 1) * kstep;
;             const char* a2 = last ? nA : cA + (size_t)(t + 2) * kstep; const char* b2 = last ? nB : cB + (size_t)(t + 2) * kstep;
;             const char* a3 = a2 + kstep; const char* b3 = b2 + kstep;
;             if (last && has_next) S.a_ready(nxt);
;             if constexpr (SP2) {
;             PG8_LDB(B0, 0, 0); PG8_LDB(B1, 0, 1); PG8_SCHED; PG8_LDA(At, 0, 0); PG8_STAGE(PG8_SA(1, 1), a1 + hstep, voffA);
;             PG8_WAIT_V(8); PG8_WAIT_L(0); PG8_BAR; PG8_MMA(0, 0, At, B0); PG8_MMA(0, 1, At, B1); PG8_BAR; PG8_SCHED;
;             PG8_LDA(At, 0, 1); PG8_STAGE(PG8_SB(0, 0), b2, voffB); PG8_STAGE(PG8_SB(0, 1), b2 + hstep, voffB); PG8_STAGE(PG8_SA(0, 0), a2, voffA);
;             PG8_WAIT_V(8); PG8_WAIT_L(0); PG8_BAR; PG8_MMA(1, 0, At, B0); PG8_MMA(1, 1, At, B1); PG8_BAR; PG8_SCHED;
.LBB0_76:
	s_add_u32 s36, s10, 0xfff80080
	s_addc_u32 s37, s11, -1
	s_add_i32 s64, 0, 0x10000
	s_cmp_eq_u32 s63, 28
	s_cselect_b32 s39, s29, s37
	s_cselect_b32 s38, s57, s36
	v_add_u32_e32 v1, s64, v153
	s_cselect_b32 s37, s27, s62
	s_cselect_b32 s36, s58, s59
	s_add_i32 s66, 0, 0x14000
	ds_read_b128 v[142:145], v1
	ds_read_b128 v[146:149], v1 offset:1024
	ds_read_b128 v[156:159], v1 offset:2048
	ds_read_b128 v[160:163], v1 offset:3072
	v_add_u32_e32 v1, s66, v153
	ds_read_b128 v[168:171], v1
	ds_read_b128 v[172:175], v1 offset:1024
	ds_read_b128 v[176:179], v1 offset:2048
	ds_read_b128 v[180:183], v1 offset:3072
	v_lshl_add_u64 v[150:151], s[10:11], 0, v[138:139]
	s_add_i32 m0, s43, 0xc000
	ds_read_b128 v[184:187], v155
	ds_read_b128 v[188:191], v155 offset:1024
	ds_read_b128 v[192:195], v155 offset:2048
	ds_read_b128 v[196:199], v155 offset:3072
	ds_read_b128 v[200:203], v155 offset:4096
	ds_read_b128 v[204:207], v155 offset:5120
	ds_read_b128 v[208:211], v155 offset:6144
	ds_read_b128 v[218:221], v155 offset:7168
	global_load_lds_dwordx4 v[150:151], off
	v_lshl_add_u64 v[150:151], s[10:11], 0, v[140:141]
	s_add_i32 m0, s43, 0xe000
	s_nop 0
	global_load_lds_dwordx4 v[150:151], off
	s_waitcnt vmcnt(8)
	s_waitcnt lgkmcnt(0)
	s_barrier
	s_setprio 1
	s_waitcnt lgkmcnt(0)
	v_mfma_f32_16x16x32_bf16 v[126:129], v[142:145], v[184:187], v[126:129]
	v_mfma_f32_16x16x32_bf16 v[122:125], v[156:159], v[184:187], v[122:125]
	v_mfma_f32_16x16x32_bf16 v[110:113], v[142:145], v[192:195], v[110:113]
	v_mfma_f32_16x16x32_bf16 v[106:109], v[156:159], v[192:195], v[106:109]
	v_mfma_f32_16x16x32_bf16 v[94:97], v[142:145], v[200:203], v[94:97]
	v_mfma_f32_16x16x32_bf16 v[90:93], v[156:159], v[200:203], v[90:93]
	v_mfma_f32_16x16x32_bf16 v[78:81], v[142:145], v[208:211], v[78:81]
	v_mfma_f32_16x16x32_bf16 v[74:77], v[156:159], v[208:211], v[74:77]
	v_mfma_f32_16x16x32_bf16 v[126:129], v[146:149], v[188:191], v[126:129]
	v_mfma_f32_16x16x32_bf16 v[122:125], v[160:163], v[188:191], v[122:125]
	v_mfma_f32_16x16x32_bf16 v[110:113], v[146:149], v[196:199], v[110:113]
	v_mfma_f32_16x16x32_bf16 v[106:109], v[160:163], v[196:199], v[106:109]
	v_mfma_f32_16x16x32_bf16 v[94:97], v[146:149], v[204:207], v[94:97]
	v_mfma_f32_16x16x32_bf16 v[90:93], v[160:163], v[204:207], v[90:93]
	v_mfma_f32_16x16x32_bf16 v[78:81], v[146:149], v[218:221], v[78:81]
	v_mfma_f32_16x16x32_bf16 v[74:77], v[160:163], v[218:221], v[74:77]
	s_setprio 0
	s_setprio 1
	v_mfma_f32_16x16x32_bf16 v[118:121], v[168:171], v[184:187], v[118:121]
	v_mfma_f32_16x16x32_bf16 v[114:117], v[176:179], v[184:187], v[114:117]
	v_mfma_f32_16x16x32_bf16 v[102:105], v[168:171], v[192:195], v[102:105]
	v_mfma_f32_16x16x32_bf16 v[98:101], v[176:179], v[192:195], v[98:101]
	v_mfma_f32_16x16x32_bf16 v[86:89], v[168:171], v[200:203], v[86:89]
	v_mfma_f32_16x16x32_bf16 v[82:85], v[176:179], v[200:203], v[82:85]
	v_mfma_f32_16x16x32_bf16 v[70:73], v[168:171], v[208:211], v[70:73]
	v_mfma_f32_16x16x32_bf16 v[66:69], v[176:179], v[208:211], v[66:69]
	v_mfma_f32_16x16x32_bf16 v[118:121], v[172:175], v[188:191], v[118:121]
	v_mfma_f32_16x16x32_bf16 v[114:117], v[180:183], v[188:191], v[114:117]
	v_mfma_f32_16x16x32_bf16 v[102:105], v[172:175], v[196:199], v[102:105]
	v_mfma_f32_16x16x32_bf16 v[98:101], v[180:183], v[196:199], v[98:101]
	v_mfma_f32_16x16x32_bf16 v[86:89], v[172:175], v[204:207], v[86:89]
	v_mfma_f32_16x16x32_bf16 v[82:85], v[180:183], v[204:207], v[82:85]
	v_mfma_f32_16x16x32_bf16 v[70:73], v[172:175], v[218:221], v[70:73]
	v_mfma_f32_16x16x32_bf16 v[66:69], v[180:183], v[218:221], v[66:69]
	s_setprio 0
	s_barrier
	s_add_i32 s64, s64, s42
	v_lshl_add_u64 v[150:151], s[36:37], 0, v[134:135]
	s_mov_b32 m0, s64
	ds_read_b128 v[184:187], v155 offset:16384
	ds_read_b128 v[188:191], v155 offset:17408
	ds_read_b128 v[192:195], v155 offset:18432
	ds_read_b128 v[196:199], v155 offset:19456
	ds_read_b128 v[200:203], v155 offset:20480
	ds_read_b128 v[204:207], v155 offset:21504
	ds_read_b128 v[208:211], v155 offset:22528
	ds_read_b128 v[218:221], v155 offset:23552
	global_load_lds_dwordx4 v[150:151], off
	s_add_i32 m0, s64, 0x2000
	s_add_u32 s64, s36, 0x80000
	v_lshl_add_u64 v[212:213], s[36:37], 0, v[130:131]
	s_addc_u32 s65, s37, 0
	s_add_i32 s66, s66, s42
	global_load_lds_dwordx4 v[212:213], off
	v_lshl_add_u64 v[226:227], s[64:65], 0, v[134:135]
	s_mov_b32 m0, s66
	v_lshl_add_u64 v[228:229], s[38:39], 0, v[132:133]
	global_load_lds_dwordx4 v[226:227], off
	v_lshl_add_u64 v[226:227], s[64:65], 0, v[130:131]
	s_add_i32 m0, s66, 0x2000
	s_nop 0
	global_load_lds_dwordx4 v[226:227], off
	v_lshl_add_u64 v[226:227], s[38:39], 0, v[136:137]
	s_mov_b32 m0, s43
	s_nop 0
	global_load_lds_dwordx4 v[226:227], off
	s_mov_b32 m0, s44
	s_nop 0
	global_load_lds_dwordx4 v[228:229], off
	s_waitcnt vmcnt(8)
	s_waitcnt lgkmcnt(0)
	s_barrier
; #define PG8_STAGE(bufoff, gbase, voff) do { _Pragma("unroll") for (int _i = 0; _i < 2; ++_i) \
;         __builtin_amdgcn_global_load_lds((const unsigned*)((const char*)(gbase) + (voff)[_i]), (PG8_LAS unsigned*)(lds + (bufoff) + ldsw + _i * 8192), 16, 0, 0); } while (0)
; #define PG8_LDA(dst, b, h) do { _Pragma("unroll") for (int m = 0; m < 4; ++m) _Pragma("unroll") for (int k = 0; k < 2; ++k) dst[m][k] = *(const PG8_LAS bf16x8*)(lds + PG8_SA(b, h) + aoff + m * 2048 + k * 1024); } while (0)
; #define PG8_LDB(dst, b, h) do { _Pragma("unroll") for (int n = 0; n < 2; ++n) _Pragma("unroll") for (int k = 0; k < 2; ++k) dst[n][k] = *(const PG8_LAS bf16x8*)(lds + PG8_SB(b, h) + boff + n * 2048 + k * 1024); } while (0)
; #define PG8_MMA(ai, bj, At, Bt) do { __builtin_amdgcn_s_setprio(1); _Pragma("unroll") for (int m = 0; m < 4; ++m) _Pragma("unroll") for (int n = 0; n < 2; ++n) _Pragma("unroll") for (int k = 0; k < 2; ++k) \
;         acc[ai][bj][m][n] = __builtin_amdgcn_mfma_f32_16x16x32_bf16(Bt[n][k], At[m][k], acc[ai][bj][m][n], 0, 0, 0); __builtin_amdgcn_s_setprio(0); } while (0)
; #define PG8_WAIT_V(n) asm volatile("s_waitcnt vmcnt(" #n ")" ::: "memory")
; #define PG8_WAIT_L(n) asm volatile("s_waitcnt lgkmcnt(" #n ")" ::: "memory")
; #define PG8_BAR __builtin_amdgcn_s_barrier()
; #define PG8_SCHED __builtin_amdgcn_sched_barrier(0)
; template <class Epi, class Sched, bool ALIGN_EPI = false, bool SP2 = false>
; __device__ __forceinline__ void gemm_phase(PG8_LAS unsigned char* lds, const Gemm g, const Sched& S, const Epi& E) {
;     ...
;             PG8_WAIT_V(8); PG8_WAIT_L(0); PG8_BAR; PG8_MMA(1, 0, At, B0); PG8_MMA(1, 1, At, B1); PG8_BAR; PG8_SCHED;
;             PG8_LDB(B0, 1, 0); PG8_LDB(B1, 1, 1); PG8_SCHED; PG8_LDA(At, 1, 0); PG8_STAGE(PG8_SA(0, 1), a2 + hstep, voffA);
;             PG8_WAIT_V(8); PG8_WAIT_L(0); PG8_BAR; PG8_MMA(0, 0, At, B0); PG8_MMA(0, 1, At, B1); PG8_BAR; PG8_SCHED;
	s_setprio 1
	s_waitcnt lgkmcnt(0)
	v_mfma_f32_16x16x32_bf16 v[62:65], v[142:145], v[184:187], v[62:65]
	v_mfma_f32_16x16x32_bf16 v[58:61], v[156:159], v[184:187], v[58:61]
	v_mfma_f32_16x16x32_bf16 v[46:49], v[142:145], v[192:195], v[46:49]
	v_mfma_f32_16x16x32_bf16 v[42:45], v[156:159], v[192:195], v[42:45]
	v_mfma_f32_16x16x32_bf16 v[30:33], v[142:145], v[200:203], v[30:33]
	v_mfma_f32_16x16x32_bf16 v[26:29], v[156:159], v[200:203], v[26:29]
	v_mfma_f32_16x16x32_bf16 v[14:17], v[142:145], v[208:211], v[14:17]
	v_mfma_f32_16x16x32_bf16 v[10:13], v[156:159], v[208:211], v[10:13]
	v_mfma_f32_16x16x32_bf16 v[62:65], v[146:149], v[188:191], v[62:65]
	v_mfma_f32_16x16x32_bf16 v[58:61], v[160:163], v[188:191], v[58:61]
	v_mfma_f32_16x16x32_bf16 v[46:49], v[146:149], v[196:199], v[46:49]
	v_mfma_f32_16x16x32_bf16 v[42:45], v[160:163], v[196:199], v[42:45]
	v_mfma_f32_16x16x32_bf16 v[30:33], v[146:149], v[204:207], v[30:33]
	v_mfma_f32_16x16x32_bf16 v[26:29], v[160:163], v[204:207], v[26:29]
	v_mfma_f32_16x16x32_bf16 v[14:17], v[146:149], v[218:221], v[14:17]
	v_mfma_f32_16x16x32_bf16 v[10:13], v[160:163], v[218:221], v[10:13]
	s_setprio 0
	s_setprio 1
	v_mfma_f32_16x16x32_bf16 v[54:57], v[168:171], v[184:187], v[54:57]
	v_mfma_f32_16x16x32_bf16 v[50:53], v[176:179], v[184:187], v[50:53]
	v_mfma_f32_16x16x32_bf16 v[38:41], v[168:171], v[192:195], v[38:41]
	v_mfma_f32_16x16x32_bf16 v[34:37], v[176:179], v[192:195], v[34:37]
	v_mfma_f32_16x16x32_bf16 v[22:25], v[168:171], v[200:203], v[22:25]
	v_mfma_f32_16x16x32_bf16 v[18:21], v[176:179], v[200:203], v[18:21]
	v_mfma_f32_16x16x32_bf16 v[6:9], v[168:171], v[208:211], v[6:9]
	v_mfma_f32_16x16x32_bf16 v[2:5], v[176:179], v[208:211], v[2:5]
	v_mfma_f32_16x16x32_bf16 v[54:57], v[172:175], v[188:191], v[54:57]
	v_mfma_f32_16x16x32_bf16 v[50:53], v[180:183], v[188:191], v[50:53]
	v_mfma_f32_16x16x32_bf16 v[38:41], v[172:175], v[196:199], v[38:41]
	v_mfma_f32_16x16x32_bf16 v[34:37], v[180:183], v[196:199], v[34:37]
	v_mfma_f32_16x16x32_bf16 v[22:25], v[172:175], v[204:207], v[22:25]
	v_mfma_f32_16x16x32_bf16 v[18:21], v[180:183], v[204:207], v[18:21]
	v_mfma_f32_16x16x32_bf16 v[6:9], v[172:175], v[218:221], v[6:9]
	v_mfma_f32_16x16x32_bf16 v[2:5], v[180:183], v[218:221], v[2:5]
	s_setprio 0
	s_barrier
	s_add_i32 s64, 0, 0x18000
	v_add_u32_e32 v1, s64, v153
	s_add_i32 s65, 0, 0x1c000
	ds_read_b128 v[142:145], v1
	ds_read_b128 v[146:149], v1 offset:1024
	ds_read_b128 v[156:159], v1 offset:2048
	ds_read_b128 v[160:163], v1 offset:3072
	v_add_u32_e32 v1, s65, v153
	ds_read_b128 v[168:171], v1
	ds_read_b128 v[172:175], v1 offset:1024
	ds_read_b128 v[176:179], v1 offset:2048
	ds_read_b128 v[180:183], v1 offset:3072
	s_add_u32 s38, s38, 0x80000
	s_addc_u32 s39, s39, 0
	s_mov_b32 m0, s45
	v_lshl_add_u64 v[230:231], s[38:39], 0, v[136:137]
	ds_read_b128 v[184:187], v155 offset:32768
	ds_read_b128 v[188:191], v155 offset:33792
	ds_read_b128 v[192:195], v155 offset:34816
	ds_read_b128 v[196:199], v155 offset:35840
	ds_read_b128 v[200:203], v155 offset:36864
	ds_read_b128 v[204:207], v155 offset:37888
	ds_read_b128 v[208:211], v155 offset:38912
	ds_read_b128 v[218:221], v155 offset:39936
	global_load_lds_dwordx4 v[230:231], off
	v_lshl_add_u64 v[230:231], s[38:39], 0, v[132:133]
	s_mov_b32 m0, s46
	s_nop 0
	global_load_lds_dwordx4 v[230:231], off
	s_waitcnt vmcnt(8)
	s_waitcnt lgkmcnt(0)
	s_barrier
	s_setprio 1
	s_waitcnt lgkmcnt(0)
	v_mfma_f32_16x16x32_bf16 v[126:129], v[142:145], v[184:187], v[126:129]
	v_mfma_f32_16x16x32_bf16 v[122:125], v[156:159], v[184:187], v[122:125]
	v_mfma_f32_16x16x32_bf16 v[110:113], v[142:145], v[192:195], v[110:113]
	v_mfma_f32_16x16x32_bf16 v[106:109], v[156:159], v[192:195], v[106:109]
	v_mfma_f32_16x16x32_bf16 v[94:97], v[142:145], v[200:203], v[94:97]
	v_mfma_f32_16x16x32_bf16 v[90:93], v[156:159], v[200:203], v[90:93]
	v_mfma_f32_16x16x32_bf16 v[78:81], v[142:145], v[208:211], v[78:81]
	v_mfma_f32_16x16x32_bf16 v[74:77], v[156:159], v[208:211], v[74:77]
	v_mfma_f32_16x16x32_bf16 v[126:129], v[146:149], v[188:191], v[126:129]
	v_mfma_f32_16x16x32_bf16 v[122:125], v[160:163], v[188:191], v[122:125]
	v_mfma_f32_16x16x32_bf16 v[110:113], v[146:149], v[196:199], v[110:113]
	v_mfma_f32_16x16x32_bf16 v[106:109], v[160:163], v[196:199], v[106:109]
	v_mfma_f32_16x16x32_bf16 v[94:97], v[146:149], v[204:207], v[94:97]
	v_mfma_f32_16x16x32_bf16 v[90:93], v[160:163], v[204:207], v[90:93]
	v_mfma_f32_16x16x32_bf16 v[78:81], v[146:149], v[218:221], v[78:81]
	v_mfma_f32_16x16x32_bf16 v[74:77], v[160:163], v[218:221], v[74:77]
	s_setprio 0
	s_setprio 1
	v_mfma_f32_16x16x32_bf16 v[118:121], v[168:171], v[184:187], v[118:121]
	v_mfma_f32_16x16x32_bf16 v[114:117], v[176:179], v[184:187], v[114:117]
	v_mfma_f32_16x16x32_bf16 v[102:105], v[168:171], v[192:195], v[102:105]
	v_mfma_f32_16x16x32_bf16 v[98:101], v[176:179], v[192:195], v[98:101]
	v_mfma_f32_16x16x32_bf16 v[86:89], v[168:171], v[200:203], v[86:89]
	v_mfma_f32_16x16x32_bf16 v[82:85], v[176:179], v[200:203], v[82:85]
	v_mfma_f32_16x16x32_bf16 v[70:73], v[168:171], v[208:211], v[70:73]
	v_mfma_f32_16x16x32_bf16 v[66:69], v[176:179], v[208:211], v[66:69]
	v_mfma_f32_16x16x32_bf16 v[118:121], v[172:175], v[188:191], v[118:121]
	v_mfma_f32_16x16x32_bf16 v[114:117], v[180:183], v[188:191], v[114:117]
	v_mfma_f32_16x16x32_bf16 v[102:105], v[172:175], v[196:199], v[102:105]
	v_mfma_f32_16x16x32_bf16 v[98:101], v[180:183], v[196:199], v[98:101]
	v_mfma_f32_16x16x32_bf16 v[86:89], v[172:175], v[204:207], v[86:89]
	v_mfma_f32_16x16x32_bf16 v[82:85], v[180:183], v[204:207], v[82:85]
	v_mfma_f32_16x16x32_bf16 v[70:73], v[172:175], v[218:221], v[70:73]
	v_mfma_f32_16x16x32_bf16 v[66:69], v[180:183], v[218:221], v[66:69]
	s_setprio 0
	s_barrier
; #define PG8_STAGE(bufoff, gbase, voff) do { _Pragma("unroll") for (int _i = 0; _i < 2; ++_i) \
;         __builtin_amdgcn_global_load_lds((const unsigned*)((const char*)(gbase) + (voff)[_i]), (PG8_LAS unsigned*)(lds + (bufoff) + ldsw + _i * 8192), 16, 0, 0); } while (0)
; #define PG8_LDA(dst, b, h) do { _Pragma("unroll") for (int m = 0; m < 4; ++m) _Pragma("unroll") for (int k = 0; k < 2; ++k) dst[m][k] = *(const PG8_LAS bf16x8*)(lds + PG8_SA(b, h) + aoff + m * 2048 + k * 1024); } while (0)
; #define PG8_MMA(ai, bj, At, Bt) do { __builtin_amdgcn_s_setprio(1); _Pragma("unroll") for (int m = 0; m < 4; ++m) _Pragma("unroll") for (int n = 0; n < 2; ++n) _Pragma("unroll") for (int k = 0; k < 2; ++k) \
;         acc[ai][bj][m][n] = __builtin_amdgcn_mfma_f32_16x16x32_bf16(Bt[n][k], At[m][k], acc[ai][bj][m][n], 0, 0, 0); __builtin_amdgcn_s_setprio(0); } while (0)
; #define PG8_WAIT_V(n) asm volatile("s_waitcnt vmcnt(" #n ")" ::: "memory")
; #define PG8_WAIT_L(n) asm volatile("s_waitcnt lgkmcnt(" #n ")" ::: "memory")
; #define PG8_BAR __builtin_amdgcn_s_barrier()
; #define PG8_SCHED __builtin_amdgcn_sched_barrier(0)
; template <class Epi, class Sched, bool ALIGN_EPI = false, bool SP2 = false>
; __device__ __forceinline__ void gemm_phase(PG8_LAS unsigned char* lds, const Gemm g, const Sched& S, const Epi& E) {
;     ...
;         for (int t = 0; t < nt; t += 2) {
;     ...
;             PG8_LDA(At, 1, 1); PG8_STAGE(PG8_SB(1, 0), b3, voffB); PG8_STAGE(PG8_SB(1, 1), b3 + hstep, voffB); PG8_STAGE(PG8_SA(1, 0), a3, voffA);
;             PG8_WAIT_V(8); PG8_WAIT_L(0); PG8_BAR; PG8_MMA(1, 0, At, B0); PG8_MMA(1, 1, At, B1); PG8_BAR; PG8_SCHED;
	s_add_i32 s38, s64, s42
	v_lshl_add_u64 v[150:151], v[150:151], 0, s[84:85]
	s_mov_b32 m0, s38
	ds_read_b128 v[184:187], v155 offset:49152
	ds_read_b128 v[188:191], v155 offset:50176
	ds_read_b128 v[192:195], v155 offset:51200
	ds_read_b128 v[196:199], v155 offset:52224
	ds_read_b128 v[200:203], v155 offset:53248
	ds_read_b128 v[204:207], v155 offset:54272
	ds_read_b128 v[208:211], v155 offset:55296
	ds_read_b128 v[218:221], v155 offset:56320
	global_load_lds_dwordx4 v[150:151], off
	s_add_i32 m0, s38, 0x2000
	s_add_u32 s36, s36, 0x80080
	v_lshl_add_u64 v[150:151], v[212:213], 0, s[84:85]
	s_addc_u32 s37, s37, 0
	s_add_i32 s38, s65, s42
	global_load_lds_dwordx4 v[150:151], off
	v_lshl_add_u64 v[150:151], s[36:37], 0, v[134:135]
	s_mov_b32 m0, s38
	s_nop 0
	global_load_lds_dwordx4 v[150:151], off
	v_lshl_add_u64 v[150:151], s[36:37], 0, v[130:131]
	s_add_i32 m0, s38, 0x2000
	s_nop 0
	global_load_lds_dwordx4 v[150:151], off
	v_lshl_add_u64 v[150:151], v[226:227], 0, s[84:85]
	s_mov_b32 m0, s47
	s_nop 0
	global_load_lds_dwordx4 v[150:151], off
	v_lshl_add_u64 v[150:151], v[228:229], 0, s[84:85]
	s_mov_b32 m0, s51
	s_nop 0
	global_load_lds_dwordx4 v[150:151], off
	s_waitcnt vmcnt(8)
	s_waitcnt lgkmcnt(0)
	s_barrier
	s_setprio 1
	s_waitcnt lgkmcnt(0)
	v_mfma_f32_16x16x32_bf16 v[62:65], v[142:145], v[184:187], v[62:65]
	v_mfma_f32_16x16x32_bf16 v[58:61], v[156:159], v[184:187], v[58:61]
	v_mfma_f32_16x16x32_bf16 v[46:49], v[142:145], v[192:195], v[46:49]
	v_mfma_f32_16x16x32_bf16 v[42:45], v[156:159], v[192:195], v[42:45]
	v_mfma_f32_16x16x32_bf16 v[30:33], v[142:145], v[200:203], v[30:33]
	v_mfma_f32_16x16x32_bf16 v[26:29], v[156:159], v[200:203], v[26:29]
	v_mfma_f32_16x16x32_bf16 v[14:17], v[142:145], v[208:211], v[14:17]
	v_mfma_f32_16x16x32_bf16 v[10:13], v[156:159], v[208:211], v[10:13]
	v_mfma_f32_16x16x32_bf16 v[62:65], v[146:149], v[188:191], v[62:65]
	v_mfma_f32_16x16x32_bf16 v[58:61], v[160:163], v[188:191], v[58:61]
	v_mfma_f32_16x16x32_bf16 v[46:49], v[146:149], v[196:199], v[46:49]
	v_mfma_f32_16x16x32_bf16 v[42:45], v[160:163], v[196:199], v[42:45]
	v_mfma_f32_16x16x32_bf16 v[30:33], v[146:149], v[204:207], v[30:33]
	v_mfma_f32_16x16x32_bf16 v[26:29], v[160:163], v[204:207], v[26:29]
	v_mfma_f32_16x16x32_bf16 v[14:17], v[146:149], v[218:221], v[14:17]
	v_mfma_f32_16x16x32_bf16 v[10:13], v[160:163], v[218:221], v[10:13]
	s_setprio 0
	s_setprio 1
	v_mfma_f32_16x16x32_bf16 v[54:57], v[168:171], v[184:187], v[54:57]
	v_mfma_f32_16x16x32_bf16 v[50:53], v[176:179], v[184:187], v[50:53]
	v_mfma_f32_16x16x32_bf16 v[38:41], v[168:171], v[192:195], v[38:41]
	v_mfma_f32_16x16x32_bf16 v[34:37], v[176:179], v[192:195], v[34:37]
	v_mfma_f32_16x16x32_bf16 v[22:25], v[168:171], v[200:203], v[22:25]
	v_mfma_f32_16x16x32_bf16 v[18:21], v[176:179], v[200:203], v[18:21]
	v_mfma_f32_16x16x32_bf16 v[6:9], v[168:171], v[208:211], v[6:9]
	v_mfma_f32_16x16x32_bf16 v[2:5], v[176:179], v[208:211], v[2:5]
	v_mfma_f32_16x16x32_bf16 v[54:57], v[172:175], v[188:191], v[54:57]
	v_mfma_f32_16x16x32_bf16 v[50:53], v[180:183], v[188:191], v[50:53]
	v_mfma_f32_16x16x32_bf16 v[38:41], v[172:175], v[196:199], v[38:41]
	v_mfma_f32_16x16x32_bf16 v[34:37], v[180:183], v[196:199], v[34:37]
	v_mfma_f32_16x16x32_bf16 v[22:25], v[172:175], v[204:207], v[22:25]
	v_mfma_f32_16x16x32_bf16 v[18:21], v[180:183], v[204:207], v[18:21]
	v_mfma_f32_16x16x32_bf16 v[6:9], v[172:175], v[218:221], v[6:9]
	v_mfma_f32_16x16x32_bf16 v[2:5], v[180:183], v[218:221], v[2:5]
	s_setprio 0
	s_barrier
	s_add_i32 s63, s63, 2
	s_add_u32 s10, s10, 0x100
	s_addc_u32 s11, s11, 0
	s_add_u32 s59, s59, 0x100
	s_addc_u32 s62, s62, 0
	s_cmp_gt_u32 s63, 29
	s_cbranch_scc0 .LBB0_76
	s_nop 0
	s_and_b64 vcc, exec, s[24:25]
	s_cbranch_vccz .LBB0_79
	s_barrier
